# diff loop: stabiliser-free fast body after tile 0 (guarded by tile row-sum with fallback to max-tracked body), exact softmax
# speedup vs baseline: 1.0177x; 1.0060x over previous
.LBB0_1234:
	s_waitcnt lgkmcnt(0)
	s_barrier
	v_mov_b32_e32 v14, v1
	v_mov_b32_e32 v15, v1
	v_mov_b32_e32 v0, v1
	v_mov_b32_e32 v2, v1
	v_mov_b32_e32 v3, v1
	v_mov_b32_e32 v4, v1
	v_mov_b32_e32 v5, v1
	v_mov_b32_e32 v6, v1
	v_mov_b32_e32 v7, v1
	v_mov_b32_e32 v8, v1
	v_mov_b32_e32 v9, v1
	v_mov_b32_e32 v10, v1
	v_mov_b32_e32 v11, v1
	v_mov_b32_e32 v12, v1
	v_mov_b32_e32 v13, v1
	v_mov_b64_e32 v[30:31], v[14:15]
	v_mov_b64_e32 v[46:47], v[14:15]
	v_mov_b64_e32 v[62:63], v[14:15]
	v_mov_b64_e32 v[78:79], v[14:15]
	s_xor_b64 s[38:39], s[8:9], -1
	v_lshl_add_u64 v[150:151], v[116:117], 1, s[40:41]
	s_mov_b32 s54, 0
	v_mov_b32_e32 v152, 0xf149f2ca
	v_mov_b32_e32 v129, 0
	v_mov_b64_e32 v[28:29], v[12:13]
	v_mov_b64_e32 v[26:27], v[10:11]
	v_mov_b64_e32 v[24:25], v[8:9]
	v_mov_b64_e32 v[22:23], v[6:7]
	v_mov_b64_e32 v[20:21], v[4:5]
	v_mov_b64_e32 v[18:19], v[2:3]
	v_mov_b64_e32 v[16:17], v[0:1]
	v_mov_b64_e32 v[44:45], v[12:13]
	v_mov_b64_e32 v[42:43], v[10:11]
	v_mov_b64_e32 v[40:41], v[8:9]
	v_mov_b64_e32 v[38:39], v[6:7]
	v_mov_b64_e32 v[36:37], v[4:5]
	v_mov_b64_e32 v[34:35], v[2:3]
	v_mov_b64_e32 v[32:33], v[0:1]
	v_mov_b64_e32 v[60:61], v[12:13]
	v_mov_b64_e32 v[58:59], v[10:11]
	v_mov_b64_e32 v[56:57], v[8:9]
	v_mov_b64_e32 v[54:55], v[6:7]
	v_mov_b64_e32 v[52:53], v[4:5]
	v_mov_b64_e32 v[50:51], v[2:3]
	v_mov_b64_e32 v[48:49], v[0:1]
	v_mov_b64_e32 v[76:77], v[12:13]
	v_mov_b64_e32 v[74:75], v[10:11]
	v_mov_b64_e32 v[72:73], v[8:9]
	v_mov_b64_e32 v[70:71], v[6:7]
	v_mov_b64_e32 v[68:69], v[4:5]
	v_mov_b64_e32 v[66:67], v[2:3]
	v_mov_b64_e32 v[64:65], v[0:1]
	s_mov_b32 s69, s76
	s_mov_b32 s99, s42
	s_mov_b32 s63, s5
	s_mov_b64 s[8:9], s[20:21]
	s_mov_b32 s78, 0
	s_mov_b32 s79, 0
	s_mov_b32 s96, 0x42200000
	s_mov_b32 s97, 0x5d800000
	s_branch .LBB0_1238

.Ldiff_redo:
	s_mul_i32 s40, s54, 0x6000
	s_add_i32 s40, s40, 0
	v_add3_u32 v0, s40, v169, v170
	v_xor_b32_e32 v2, 32, v171
	v_xor_b32_e32 v3, 64, v171
	v_add_u32_e32 v10, v0, v171
	v_add_u32_e32 v11, v0, v2
	v_add_u32_e32 v12, v0, v3
	v_add_u32_e32 v13, v0, v172
	ds_read_b128 v[192:195], v10
	ds_read_b128 v[196:199], v10 offset:4096
	ds_read_b128 v[200:203], v11
	ds_read_b128 v[204:207], v11 offset:4096
	ds_read_b128 v[208:211], v12
	ds_read_b128 v[212:215], v12 offset:4096
	ds_read_b128 v[216:219], v13
	ds_read_b128 v[220:223], v13 offset:4096
	s_sub_i32 s50, s72, s41
	s_cmpk_gt_i32 s50, 0x70
	s_waitcnt lgkmcnt(7)
	v_mfma_f32_32x32x16_bf16 v[96:111], v[192:195], v[224:227], 0
	s_waitcnt lgkmcnt(6)
	v_mfma_f32_32x32x16_bf16 v[80:95], v[196:199], v[224:227], 0
	s_waitcnt lgkmcnt(5)
	v_mfma_f32_32x32x16_bf16 v[96:111], v[200:203], v[228:231], v[96:111]
	s_waitcnt lgkmcnt(4)
	v_mfma_f32_32x32x16_bf16 v[80:95], v[204:207], v[228:231], v[80:95]
	s_waitcnt lgkmcnt(3)
	v_mfma_f32_32x32x16_bf16 v[96:111], v[208:211], v[232:235], v[96:111]
	s_waitcnt lgkmcnt(2)
	v_mfma_f32_32x32x16_bf16 v[80:95], v[212:215], v[232:235], v[80:95]
	s_waitcnt lgkmcnt(1)
	v_mfma_f32_32x32x16_bf16 v[96:111], v[216:219], v[236:239], v[96:111]
	s_waitcnt lgkmcnt(0)
	v_mfma_f32_32x32x16_bf16 v[80:95], v[220:223], v[236:239], v[80:95]
	s_cbranch_scc1 .LBB0_1241
	v_or_b32_e32 v0, s41, v122
	v_sub_u32_e32 v0, v128, v0
	v_add_u32_e32 v153, -1, v0
	v_subrev_u32_e32 v178, 33, v0
	v_subrev_u32_e32 v179, 32, v0
	v_subrev_u32_e32 v198, 34, v0
	v_med3_i32 v2, v0, 0, v181
	v_med3_i32 v3, v153, 0, v181
	v_med3_i32 v4, v179, 0, v181
	v_med3_i32 v5, v178, 0, v181
	v_add_u32_e32 v191, -3, v0
	v_add_u32_e32 v196, -2, v0
	v_subrev_u32_e32 v197, 35, v0
	v_med3_i32 v8, v198, 0, v181
	v_lshl_add_u32 v2, v2, 2, s82
	v_lshl_add_u32 v3, v3, 2, s82
	v_lshl_add_u32 v4, v4, 2, s82
	v_lshl_add_u32 v5, v5, 2, s82
	v_med3_i32 v6, v196, 0, v181
	v_med3_i32 v7, v191, 0, v181
	v_lshl_add_u32 v12, v8, 2, s82
	v_med3_i32 v8, v197, 0, v181
	v_lshl_add_u32 v6, v6, 2, s82
	v_lshl_add_u32 v7, v7, 2, s82
	v_lshl_add_u32 v13, v8, 2, s82
	ds_read_b32 v8, v2
	ds_read_b32 v9, v3
	ds_read_b32 v4, v4
	ds_read_b32 v5, v5
	ds_read_b32 v10, v6
	ds_read_b32 v11, v7
	ds_read_b32 v2, v12
	ds_read_b32 v3, v13
	v_subrev_u32_e32 v202, 40, v0
	v_subrev_u32_e32 v201, 41, v0
	v_med3_i32 v12, v202, 0, v181
	v_lshl_add_u32 v14, v12, 2, s82
	v_med3_i32 v12, v201, 0, v181
	v_add_u32_e32 v204, -10, v0
	v_lshl_add_u32 v15, v12, 2, s82
	v_add_u32_e32 v203, -11, v0
	v_med3_i32 v12, v204, 0, v181
	v_add_u32_e32 v199, -9, v0
	v_add_u32_e32 v200, -8, v0
	v_lshl_add_u32 v154, v12, 2, s82
	v_med3_i32 v12, v203, 0, v181
	v_subrev_u32_e32 v206, 42, v0
	v_med3_i32 v6, v200, 0, v181
	v_med3_i32 v7, v199, 0, v181
	v_lshl_add_u32 v155, v12, 2, s82
	v_subrev_u32_e32 v205, 43, v0
	v_med3_i32 v12, v206, 0, v181
	v_lshl_add_u32 v6, v6, 2, s82
	v_lshl_add_u32 v7, v7, 2, s82
	v_lshl_add_u32 v156, v12, 2, s82
	v_med3_i32 v12, v205, 0, v181
	v_lshl_add_u32 v157, v12, 2, s82
	ds_read_b32 v12, v6
	ds_read_b32 v13, v7
	ds_read_b32 v14, v14
	ds_read_b32 v15, v15
	ds_read_b32 v154, v154
	ds_read_b32 v155, v155
	ds_read_b32 v6, v156
	ds_read_b32 v7, v157
	v_subrev_u32_e32 v207, 17, v0
	v_add_u32_e32 v208, -16, v0
	v_subrev_u32_e32 v209, 49, v0
	v_subrev_u32_e32 v210, 48, v0
	v_subrev_u32_e32 v211, 19, v0
	v_subrev_u32_e32 v212, 18, v0
	v_subrev_u32_e32 v213, 51, v0
	v_subrev_u32_e32 v214, 50, v0
	v_med3_i32 v156, v208, 0, v181
	v_med3_i32 v157, v207, 0, v181
	v_med3_i32 v158, v210, 0, v181
	v_med3_i32 v159, v209, 0, v181
	v_med3_i32 v160, v212, 0, v181
	v_med3_i32 v161, v211, 0, v181
	v_med3_i32 v162, v214, 0, v181
	v_med3_i32 v163, v213, 0, v181
	v_lshl_add_u32 v156, v156, 2, s82
	v_lshl_add_u32 v157, v157, 2, s82
	v_lshl_add_u32 v158, v158, 2, s82
	v_lshl_add_u32 v159, v159, 2, s82
	v_lshl_add_u32 v160, v160, 2, s82
	v_lshl_add_u32 v161, v161, 2, s82
	v_lshl_add_u32 v162, v162, 2, s82
	v_lshl_add_u32 v163, v163, 2, s82
	ds_read_b32 v156, v156
	ds_read_b32 v157, v157
	ds_read_b32 v158, v158
	ds_read_b32 v159, v159
	ds_read_b32 v160, v160
	ds_read_b32 v161, v161
	ds_read_b32 v162, v162
	ds_read_b32 v163, v163
	s_waitcnt lgkmcnt(14)
	v_pk_add_f32 v[10:11], v[98:99], v[10:11]
	v_cmp_gt_u32_e32 vcc, 2.0, v191
	v_pk_add_f32 v[8:9], v[96:97], v[8:9]
	v_pk_add_f32 v[12:13], v[100:101], v[12:13]
	v_cndmask_b32_e32 v99, v182, v11, vcc
	v_cmp_gt_u32_e32 vcc, 2.0, v196
	s_waitcnt lgkmcnt(10)
	v_pk_add_f32 v[100:101], v[102:103], v[154:155]
	v_subrev_u32_e32 v215, 25, v0
	v_cndmask_b32_e32 v98, v182, v10, vcc
	v_cmp_gt_u32_e32 vcc, 2.0, v153
	v_subrev_u32_e32 v216, 24, v0
	v_subrev_u32_e32 v217, 57, v0
	v_cndmask_b32_e32 v97, v182, v9, vcc
	v_cmp_gt_u32_e32 vcc, 2.0, v0
	v_subrev_u32_e32 v218, 56, v0
	v_subrev_u32_e32 v219, 27, v0
	v_cndmask_b32_e32 v96, v182, v8, vcc
	v_cmp_gt_u32_e32 vcc, 2.0, v203
	v_subrev_u32_e32 v220, 26, v0
	v_subrev_u32_e32 v221, 59, v0
	v_cndmask_b32_e32 v103, v182, v101, vcc
	v_cmp_gt_u32_e32 vcc, 2.0, v204
	v_subrev_u32_e32 v222, 58, v0
	v_med3_i32 v164, v216, 0, v181
	v_cndmask_b32_e32 v102, v182, v100, vcc
	v_cmp_gt_u32_e32 vcc, 2.0, v199
	v_med3_i32 v165, v215, 0, v181
	v_med3_i32 v166, v218, 0, v181
	v_cndmask_b32_e32 v101, v182, v13, vcc
	v_cmp_gt_u32_e32 vcc, 2.0, v200
	v_med3_i32 v167, v217, 0, v181
	v_med3_i32 v192, v220, 0, v181
	v_med3_i32 v193, v219, 0, v181
	v_med3_i32 v194, v222, 0, v181
	v_med3_i32 v195, v221, 0, v181
	s_waitcnt lgkmcnt(2)
	v_pk_add_f32 v[106:107], v[106:107], v[160:161]
	v_cndmask_b32_e32 v100, v182, v12, vcc
	v_cmp_gt_u32_e32 vcc, 2.0, v211
	v_lshl_add_u32 v164, v164, 2, s82
	v_lshl_add_u32 v165, v165, 2, s82
	v_lshl_add_u32 v166, v166, 2, s82
	v_lshl_add_u32 v167, v167, 2, s82
	v_lshl_add_u32 v192, v192, 2, s82
	v_lshl_add_u32 v193, v193, 2, s82
	v_lshl_add_u32 v194, v194, 2, s82
	v_lshl_add_u32 v195, v195, 2, s82
	v_cndmask_b32_e32 v107, v182, v107, vcc
	v_cmp_gt_u32_e32 vcc, 2.0, v212
	ds_read_b32 v164, v164
	ds_read_b32 v165, v165
	ds_read_b32 v166, v166
	ds_read_b32 v192, v192
	ds_read_b32 v193, v193
	ds_read_b32 v194, v194
	ds_read_b32 v195, v195
	ds_read_b32 v167, v167
	v_pk_add_f32 v[104:105], v[104:105], v[156:157]
	v_cndmask_b32_e32 v106, v182, v106, vcc
	v_cmp_gt_u32_e32 vcc, 2.0, v207
	s_waitcnt lgkmcnt(3)
	v_pk_add_f32 v[110:111], v[110:111], v[192:193]
	v_pk_add_f32 v[108:109], v[108:109], v[164:165]
	v_cndmask_b32_e32 v105, v182, v105, vcc
	v_cmp_gt_u32_e32 vcc, 2.0, v208
	v_pk_add_f32 v[2:3], v[82:83], v[2:3]
	v_pk_add_f32 v[4:5], v[80:81], v[4:5]
	v_cndmask_b32_e32 v104, v182, v104, vcc
	v_cmp_gt_u32_e32 vcc, 2.0, v219
	v_pk_add_f32 v[6:7], v[86:87], v[6:7]
	v_pk_add_f32 v[14:15], v[84:85], v[14:15]
	v_cndmask_b32_e32 v111, v182, v111, vcc
	v_cmp_gt_u32_e32 vcc, 2.0, v220
	v_pk_add_f32 v[12:13], v[88:89], v[158:159]
	v_pk_add_f32 v[88:89], v[90:91], v[162:163]
	v_cndmask_b32_e32 v110, v182, v110, vcc
	v_cmp_gt_u32_e32 vcc, 2.0, v215
	s_waitcnt lgkmcnt(1)
	v_pk_add_f32 v[10:11], v[94:95], v[194:195]
	s_waitcnt lgkmcnt(0)
	v_pk_add_f32 v[8:9], v[92:93], v[166:167]
	v_cndmask_b32_e32 v109, v182, v109, vcc
	v_cmp_gt_u32_e32 vcc, 2.0, v216
	s_nop 1
	v_cndmask_b32_e32 v108, v182, v108, vcc
	v_cmp_gt_u32_e32 vcc, 2.0, v197
	s_nop 1
	v_cndmask_b32_e32 v83, v182, v3, vcc
	v_cmp_gt_u32_e32 vcc, 2.0, v198
	s_nop 1
	v_cndmask_b32_e32 v82, v182, v2, vcc
	v_cmp_gt_u32_e32 vcc, 2.0, v178
	s_nop 1
	v_cndmask_b32_e32 v81, v182, v5, vcc
	v_cmp_gt_u32_e32 vcc, 2.0, v179
	s_nop 1
	v_cndmask_b32_e32 v80, v182, v4, vcc
	v_cmp_gt_u32_e32 vcc, 2.0, v205
	s_nop 1
	v_cndmask_b32_e32 v87, v182, v7, vcc
	v_cmp_gt_u32_e32 vcc, 2.0, v206
	s_nop 1
	v_cndmask_b32_e32 v86, v182, v6, vcc
	v_cmp_gt_u32_e32 vcc, 2.0, v201
	s_nop 1
	v_cndmask_b32_e32 v85, v182, v15, vcc
	v_cmp_gt_u32_e32 vcc, 2.0, v202
	s_nop 1
	v_cndmask_b32_e32 v84, v182, v14, vcc
	v_cmp_gt_u32_e32 vcc, 2.0, v213
	s_nop 1
	v_cndmask_b32_e32 v91, v182, v89, vcc
	v_cmp_gt_u32_e32 vcc, 2.0, v214
	s_nop 1
	v_cndmask_b32_e32 v90, v182, v88, vcc
	v_cmp_gt_u32_e32 vcc, 2.0, v209
	s_nop 1
	v_cndmask_b32_e32 v89, v182, v13, vcc
	v_cmp_gt_u32_e32 vcc, 2.0, v210
	s_nop 1
	v_cndmask_b32_e32 v88, v182, v12, vcc
	v_cmp_gt_u32_e32 vcc, 2.0, v221
	s_nop 1
	v_cndmask_b32_e32 v95, v182, v11, vcc
	v_cmp_gt_u32_e32 vcc, 2.0, v222
	s_nop 1
	v_cndmask_b32_e32 v94, v182, v10, vcc
	v_cmp_gt_u32_e32 vcc, 2.0, v217
	s_nop 1
	v_cndmask_b32_e32 v93, v182, v9, vcc
	v_cmp_gt_u32_e32 vcc, 2.0, v218
	s_nop 1
	v_cndmask_b32_e32 v92, v182, v8, vcc
.LBB0_1241:
	v_add3_u32 v2, s40, v173, v174
	v_add3_u32 v2, v2, v175, v184
	v_add_u32_e32 v158, v2, v185
	v_add_u32_e32 v159, v2, v186
	v_add_u32_e32 v160, v2, v187
	v_add_u32_e32 v161, v2, v188
	ds_read_b64_tr_b16 v[192:193], v158 offset:8192
	ds_read_b64_tr_b16 v[194:195], v158 offset:10240
	ds_read_b64_tr_b16 v[196:197], v159 offset:8192
	ds_read_b64_tr_b16 v[198:199], v159 offset:10240
	ds_read_b64_tr_b16 v[200:201], v160 offset:8192
	ds_read_b64_tr_b16 v[202:203], v160 offset:10240
	ds_read_b64_tr_b16 v[204:205], v161 offset:8192
	ds_read_b64_tr_b16 v[206:207], v161 offset:10240
	s_cmp_lg_u32 s78, 0
	s_cbranch_scc1 .Ldiff_fast
	v_max3_f32 v0, v96, v97, v98
	v_max3_f32 v2, v99, v100, v101
	v_max3_f32 v3, v102, v103, v104
	v_max3_f32 v4, v105, v106, v107
	v_max3_f32 v0, v0, v108, v109
	v_max3_f32 v2, v2, v110, v111
	v_max3_f32 v3, v3, v80, v81
	v_max3_f32 v4, v4, v82, v83
	v_max3_f32 v0, v0, v84, v85
	v_max3_f32 v2, v2, v86, v87
	v_max3_f32 v3, v3, v88, v89
	v_max3_f32 v4, v4, v90, v91
	v_max3_f32 v0, v0, v92, v93
	v_max3_f32 v2, v2, v94, v95
	v_max3_f32 v0, v0, v3, v4
	v_max_f32_e32 v0, v0, v2
	v_mov_b32_e32 v2, v0
	s_nop 1
	v_permlane32_swap_b32 v0, v2
	s_nop 0
	v_max_f32_e32 v3, v0, v2
	v_sub_f32_e32 v0, v3, v152
	v_cmp_lt_f32_e32 vcc, 0x41000000, v0
	s_cbranch_vccnz .Ldiff_rescale

.Ldiff_pv:
	s_waitcnt lgkmcnt(8)
	v_mfma_f32_32x32x16_bf16 v[64:79], v[192:195], v[240:243], v[64:79]
	ds_read_b64_tr_b16 v[192:193], v158 offset:16384
	ds_read_b64_tr_b16 v[194:195], v158 offset:18432
	v_mfma_f32_32x32x16_bf16 v[48:63], v[196:199], v[240:243], v[48:63]
	ds_read_b64_tr_b16 v[196:197], v159 offset:16384
	ds_read_b64_tr_b16 v[198:199], v159 offset:18432
	v_mfma_f32_32x32x16_bf16 v[32:47], v[200:203], v[240:243], v[32:47]
	ds_read_b64_tr_b16 v[200:201], v160 offset:16384
	ds_read_b64_tr_b16 v[202:203], v160 offset:18432
	v_mfma_f32_32x32x16_bf16 v[16:31], v[204:207], v[240:243], v[16:31]
	ds_read_b64_tr_b16 v[204:205], v161 offset:16384
	ds_read_b64_tr_b16 v[206:207], v161 offset:18432
	s_waitcnt lgkmcnt(8)
	v_mfma_f32_32x32x16_bf16 v[64:79], v[208:211], v[244:247], v[64:79]
	ds_read_b64_tr_b16 v[208:209], v158 offset:20480
	ds_read_b64_tr_b16 v[210:211], v158 offset:22528
	v_mfma_f32_32x32x16_bf16 v[48:63], v[212:215], v[244:247], v[48:63]
	ds_read_b64_tr_b16 v[212:213], v159 offset:20480
	ds_read_b64_tr_b16 v[214:215], v159 offset:22528
	v_mfma_f32_32x32x16_bf16 v[32:47], v[216:219], v[244:247], v[32:47]
	ds_read_b64_tr_b16 v[216:217], v160 offset:20480
	ds_read_b64_tr_b16 v[218:219], v160 offset:22528
	v_mfma_f32_32x32x16_bf16 v[16:31], v[220:223], v[244:247], v[16:31]
	ds_read_b64_tr_b16 v[220:221], v161 offset:20480
	ds_read_b64_tr_b16 v[222:223], v161 offset:22528
	s_waitcnt lgkmcnt(8)
	v_mfma_f32_32x32x16_bf16 v[64:79], v[192:195], v[248:251], v[64:79]
	v_mfma_f32_32x32x16_bf16 v[48:63], v[196:199], v[248:251], v[48:63]
	v_mfma_f32_32x32x16_bf16 v[32:47], v[200:203], v[248:251], v[32:47]
	v_mfma_f32_32x32x16_bf16 v[16:31], v[204:207], v[248:251], v[16:31]
	s_waitcnt lgkmcnt(0)
	v_mfma_f32_32x32x16_bf16 v[64:79], v[208:211], v[154:157], v[64:79]
	v_mfma_f32_32x32x16_bf16 v[48:63], v[212:215], v[154:157], v[48:63]
	v_mfma_f32_32x32x16_bf16 v[32:47], v[216:219], v[154:157], v[32:47]
	v_mfma_f32_32x32x16_bf16 v[16:31], v[220:223], v[154:157], v[16:31]
	s_cmp_lg_u32 s79, 0
	s_cbranch_scc1 .LBB0_1242
	s_mov_b32 s79, 1
	v_cmp_gt_f32_e64 vcc, |v152|, s96
	s_cbranch_vccnz .LBB0_1242
	s_nop 11
	v_exp_f32_e32 v0, v152
	v_mov_b32_e32 v152, 0
	s_mov_b32 s78, 1
	v_mul_f32_e32 v129, v129, v0
	v_mul_f32_e32 v16, v16, v0
	v_mul_f32_e32 v17, v17, v0
	v_mul_f32_e32 v18, v18, v0
	v_mul_f32_e32 v19, v19, v0
	v_mul_f32_e32 v20, v20, v0
	v_mul_f32_e32 v21, v21, v0
	v_mul_f32_e32 v22, v22, v0
	v_mul_f32_e32 v23, v23, v0
	v_mul_f32_e32 v24, v24, v0
	v_mul_f32_e32 v25, v25, v0
	v_mul_f32_e32 v26, v26, v0
	v_mul_f32_e32 v27, v27, v0
	v_mul_f32_e32 v28, v28, v0
	v_mul_f32_e32 v29, v29, v0
	v_mul_f32_e32 v30, v30, v0
	v_mul_f32_e32 v31, v31, v0
	v_mul_f32_e32 v32, v32, v0
	v_mul_f32_e32 v33, v33, v0
	v_mul_f32_e32 v34, v34, v0
	v_mul_f32_e32 v35, v35, v0
	v_mul_f32_e32 v36, v36, v0
	v_mul_f32_e32 v37, v37, v0
	v_mul_f32_e32 v38, v38, v0
	v_mul_f32_e32 v39, v39, v0
	v_mul_f32_e32 v40, v40, v0
	v_mul_f32_e32 v41, v41, v0
	v_mul_f32_e32 v42, v42, v0
	v_mul_f32_e32 v43, v43, v0
	v_mul_f32_e32 v44, v44, v0
	v_mul_f32_e32 v45, v45, v0
	v_mul_f32_e32 v46, v46, v0
	v_mul_f32_e32 v47, v47, v0
	v_mul_f32_e32 v48, v48, v0
	v_mul_f32_e32 v49, v49, v0
	v_mul_f32_e32 v50, v50, v0
	v_mul_f32_e32 v51, v51, v0
	v_mul_f32_e32 v52, v52, v0
	v_mul_f32_e32 v53, v53, v0
	v_mul_f32_e32 v54, v54, v0
	v_mul_f32_e32 v55, v55, v0
	v_mul_f32_e32 v56, v56, v0
	v_mul_f32_e32 v57, v57, v0
	v_mul_f32_e32 v58, v58, v0
	v_mul_f32_e32 v59, v59, v0
	v_mul_f32_e32 v60, v60, v0
	v_mul_f32_e32 v61, v61, v0
	v_mul_f32_e32 v62, v62, v0
	v_mul_f32_e32 v63, v63, v0
	v_mul_f32_e32 v64, v64, v0
	v_mul_f32_e32 v65, v65, v0
	v_mul_f32_e32 v66, v66, v0
	v_mul_f32_e32 v67, v67, v0
	v_mul_f32_e32 v68, v68, v0
	v_mul_f32_e32 v69, v69, v0
	v_mul_f32_e32 v70, v70, v0
	v_mul_f32_e32 v71, v71, v0
	v_mul_f32_e32 v72, v72, v0
	v_mul_f32_e32 v73, v73, v0
	v_mul_f32_e32 v74, v74, v0
	v_mul_f32_e32 v75, v75, v0
	v_mul_f32_e32 v76, v76, v0
	v_mul_f32_e32 v77, v77, v0
	v_mul_f32_e32 v78, v78, v0
	v_mul_f32_e32 v79, v79, v0
	s_branch .LBB0_1242
.Ldiff_fast:
	v_exp_f32_e32 v96, v96
	v_exp_f32_e32 v97, v97
	v_exp_f32_e32 v98, v98
	v_exp_f32_e32 v99, v99
	v_exp_f32_e32 v100, v100
	v_exp_f32_e32 v101, v101
	v_exp_f32_e32 v102, v102
	v_exp_f32_e32 v103, v103
	v_cvt_pk_bf16_f32 v240, v96, v97
	v_cvt_pk_bf16_f32 v241, v98, v99
	v_exp_f32_e32 v104, v104
	v_exp_f32_e32 v105, v105
	v_exp_f32_e32 v106, v106
	v_exp_f32_e32 v107, v107
	v_add_f32_e32 v6, v96, v100
	v_add_f32_e32 v7, v97, v101
	v_add_f32_e32 v8, v98, v102
	v_add_f32_e32 v9, v99, v103
	v_cvt_pk_bf16_f32 v242, v100, v101
	v_cvt_pk_bf16_f32 v243, v102, v103
	v_exp_f32_e32 v108, v108
	v_exp_f32_e32 v109, v109
	v_exp_f32_e32 v110, v110
	v_exp_f32_e32 v111, v111
	v_add_f32_e32 v6, v6, v104
	v_add_f32_e32 v7, v7, v105
	v_add_f32_e32 v8, v8, v106
	v_add_f32_e32 v9, v9, v107
	v_cvt_pk_bf16_f32 v244, v104, v105
	v_cvt_pk_bf16_f32 v245, v106, v107
	ds_read_b64_tr_b16 v[208:209], v158 offset:12288
	ds_read_b64_tr_b16 v[210:211], v158 offset:14336
	ds_read_b64_tr_b16 v[212:213], v159 offset:12288
	ds_read_b64_tr_b16 v[214:215], v159 offset:14336
	ds_read_b64_tr_b16 v[216:217], v160 offset:12288
	ds_read_b64_tr_b16 v[218:219], v160 offset:14336
	ds_read_b64_tr_b16 v[220:221], v161 offset:12288
	ds_read_b64_tr_b16 v[222:223], v161 offset:14336
	v_exp_f32_e32 v80, v80
	v_exp_f32_e32 v81, v81
	v_exp_f32_e32 v82, v82
	v_exp_f32_e32 v83, v83
	v_add_f32_e32 v6, v6, v108
	v_add_f32_e32 v7, v7, v109
	v_add_f32_e32 v8, v8, v110
	v_add_f32_e32 v9, v9, v111
	v_cvt_pk_bf16_f32 v246, v108, v109
	v_cvt_pk_bf16_f32 v247, v110, v111
	v_exp_f32_e32 v84, v84
	v_exp_f32_e32 v85, v85
	v_exp_f32_e32 v86, v86
	v_exp_f32_e32 v87, v87
	v_add_f32_e32 v6, v6, v80
	v_add_f32_e32 v7, v7, v81
	v_add_f32_e32 v8, v8, v82
	v_add_f32_e32 v9, v9, v83
	v_cvt_pk_bf16_f32 v248, v80, v81
	v_cvt_pk_bf16_f32 v249, v82, v83
	v_exp_f32_e32 v88, v88
	v_exp_f32_e32 v89, v89
	v_exp_f32_e32 v90, v90
	v_exp_f32_e32 v91, v91
	v_add_f32_e32 v6, v6, v84
	v_add_f32_e32 v7, v7, v85
	v_add_f32_e32 v8, v8, v86
	v_add_f32_e32 v9, v9, v87
	v_cvt_pk_bf16_f32 v250, v84, v85
	v_cvt_pk_bf16_f32 v251, v86, v87
	v_exp_f32_e32 v92, v92
	v_exp_f32_e32 v93, v93
	v_exp_f32_e32 v94, v94
	v_exp_f32_e32 v95, v95
	v_add_f32_e32 v6, v6, v88
	v_add_f32_e32 v7, v7, v89
	v_add_f32_e32 v8, v8, v90
	v_add_f32_e32 v9, v9, v91
	v_cvt_pk_bf16_f32 v154, v88, v89
	v_cvt_pk_bf16_f32 v155, v90, v91
	v_add_f32_e32 v6, v6, v92
	v_add_f32_e32 v7, v7, v93
	v_add_f32_e32 v8, v8, v94
	v_add_f32_e32 v9, v9, v95
	v_cvt_pk_bf16_f32 v156, v92, v93
	v_cvt_pk_bf16_f32 v157, v94, v95
	v_add_f32_e32 v6, v6, v7
	v_add_f32_e32 v8, v8, v9
	v_add_f32_e32 v6, v6, v8
	v_cmp_lt_f32_e32 vcc, s97, v6
	s_cbranch_vccnz .Ldiff_fallback
	v_add_f32_e32 v129, v129, v6
	s_branch .Ldiff_pv
.Ldiff_fallback:
	s_mov_b32 s78, 0
	v_mov_b32_e32 v152, 0
	s_branch .Ldiff_redo
